# scan chunk body: scalar f32 VALU instead of packed f32 (same math)
# baseline (speedup 1.0000x reference)
.LBB0_1092:
	s_mov_b64 s[92:93], -1
	s_and_b64 vcc, exec, s[88:89]
	s_cbranch_vccz .LBB0_1098
	s_bitcmp1_b32 s9, 0
	s_cselect_b32 s7, 0xb200, 0
	s_add_i32 s26, s7, 0
	s_mov_b64 s[82:83], s[96:97]
	s_mov_b32 s84, s80
	v_lshl_add_u32 v174, v102, 2, s26
	v_mov_b32_e32 v175, s26
	v_add_u32_e32 v163, s26, v160
	v_mov_b64_e32 v[144:145], v[140:141]
	v_mov_b64_e32 v[146:147], v[142:143]
	v_mov_b32_e32 v162, v111
	ds_read_b128 v[0:3], v174 offset:0
	ds_read_b128 v[4:7], v174 offset:256
	ds_read_b128 v[8:11], v174 offset:512
	ds_read_b128 v[12:15], v174 offset:768
	ds_read_b128 v[16:19], v174 offset:1024
	ds_read_b128 v[20:23], v174 offset:1280
	ds_read_b128 v[24:27], v174 offset:1536
	ds_read_b128 v[28:31], v174 offset:1792
	ds_read_b128 v[32:35], v174 offset:2048
	ds_read_b128 v[36:39], v175 offset:2816
	ds_read_b32 v40, v163 offset:2304
	ds_read_b32 v41, v163 offset:2560
	s_waitcnt lgkmcnt(0)
	v_mul_f32_e32 v96, v144, v50
	v_mul_f32_e32 v97, v145, v51
	v_mul_f32_e32 v98, v144, v0
	v_mul_f32_e32 v99, v145, v1
	v_mul_f32_e32 v100, v144, v4
	v_mul_f32_e32 v101, v145, v5
	v_mul_f32_e32 v172, v144, v8
	v_mul_f32_e32 v173, v145, v9
	v_fmac_f32_e32 v96, v146, v52
	v_fmac_f32_e32 v97, v147, v53
	v_fmac_f32_e32 v98, v146, v2
	v_fmac_f32_e32 v99, v147, v3
	v_fmac_f32_e32 v100, v146, v6
	v_fmac_f32_e32 v101, v147, v7
	v_fmac_f32_e32 v172, v146, v10
	v_fmac_f32_e32 v173, v147, v11
	ds_read_b128 v[54:57], v174 offset:2848
	ds_read_b128 v[58:61], v174 offset:3104
	ds_read_b128 v[62:65], v174 offset:3360
	ds_read_b128 v[66:69], v174 offset:3616
	ds_read_b128 v[70:73], v174 offset:3872
	ds_read_b128 v[74:77], v174 offset:4128
	ds_read_b128 v[78:81], v174 offset:4384
	ds_read_b128 v[82:85], v174 offset:4640
	ds_read_b128 v[86:89], v174 offset:4896
	ds_read_b128 v[90:93], v175 offset:5664
	ds_read_b32 v94, v163 offset:5152
	ds_read_b32 v95, v163 offset:5408
	v_mul_f32_e32 v148, v24, v40
	v_mul_f32_e32 v149, v25, v40
	v_mul_f32_e32 v150, v26, v40
	v_mul_f32_e32 v151, v27, v40
	v_add_f32_e32 v168, v96, v97
	v_add_f32_e32 v166, v98, v99
	v_add_f32_e32 v169, v100, v101
	v_add_f32_e32 v170, v172, v173
	v_fmac_f32_e32 v148, v32, v41
	v_fmac_f32_e32 v149, v33, v41
	v_fmac_f32_e32 v150, v34, v41
	v_fmac_f32_e32 v151, v35, v41
	v_add_f32_dpp v168, v168, v168 row_mirror row_mask:0xf bank_mask:0xf bound_ctrl:1
	v_add_f32_dpp v166, v166, v166 row_mirror row_mask:0xf bank_mask:0xf bound_ctrl:1
	v_add_f32_dpp v169, v169, v169 row_mirror row_mask:0xf bank_mask:0xf bound_ctrl:1
	v_add_f32_dpp v170, v170, v170 row_mirror row_mask:0xf bank_mask:0xf bound_ctrl:1
	v_add_f32_dpp v168, v168, v168 row_half_mirror row_mask:0xf bank_mask:0xf bound_ctrl:1
	v_add_f32_dpp v166, v166, v166 row_half_mirror row_mask:0xf bank_mask:0xf bound_ctrl:1
	v_add_f32_dpp v169, v169, v169 row_half_mirror row_mask:0xf bank_mask:0xf bound_ctrl:1
	v_add_f32_dpp v170, v170, v170 row_half_mirror row_mask:0xf bank_mask:0xf bound_ctrl:1
	v_add_f32_dpp v168, v168, v168 quad_perm:[1,0,3,2] row_mask:0xf bank_mask:0xf bound_ctrl:1
	v_add_f32_dpp v166, v166, v166 quad_perm:[1,0,3,2] row_mask:0xf bank_mask:0xf bound_ctrl:1
	v_add_f32_dpp v169, v169, v169 quad_perm:[1,0,3,2] row_mask:0xf bank_mask:0xf bound_ctrl:1
	v_add_f32_dpp v170, v170, v170 quad_perm:[1,0,3,2] row_mask:0xf bank_mask:0xf bound_ctrl:1
	v_add_f32_dpp v168, v168, v168 quad_perm:[2,3,0,1] row_mask:0xf bank_mask:0xf bound_ctrl:1
	v_add_f32_dpp v166, v166, v166 quad_perm:[2,3,0,1] row_mask:0xf bank_mask:0xf bound_ctrl:1
	v_add_f32_dpp v169, v169, v169 quad_perm:[2,3,0,1] row_mask:0xf bank_mask:0xf bound_ctrl:1
	v_add_f32_dpp v170, v170, v170 quad_perm:[2,3,0,1] row_mask:0xf bank_mask:0xf bound_ctrl:1
	v_fma_f32 v164, v40, v37, v169
	v_fma_f32 v171, v40, v39, v170
	v_fmac_f32_e32 v148, v20, v166
	v_fmac_f32_e32 v149, v21, v166
	v_fma_f32 v167, v166, v36, v164
	v_fmac_f32_e32 v150, v22, v166
	v_fmac_f32_e32 v151, v23, v166
	v_fma_f32 v171, v166, v38, v171
	v_cndmask_b32_e64 v162, v162, v168, s[46:47]
	s_lshl_b32 s6, s9, 1
	s_cmp_eq_u32 s6, 0
	s_cbranch_scc1 .Lscan_noy0
	s_add_i32 s6, s6, -1
	s_and_b32 s6, s6, 7
	s_lshl_b32 s6, s6, 10
	v_add_u32_e32 v161, s6, v156
	ds_write_b32 v161, v162
.Lscan_noy0:
	v_fmac_f32_e32 v148, v28, v167
	v_fmac_f32_e32 v149, v29, v167
	v_fmac_f32_e32 v150, v30, v167
	v_fmac_f32_e32 v151, v31, v167
	v_cndmask_b32_e64 v162, v162, v171, s[38:39]
	v_fma_f32 v144, v144, v16, v148
	v_fma_f32 v145, v145, v17, v149
	v_fma_f32 v146, v146, v18, v150
	v_fma_f32 v147, v147, v19, v151
	s_waitcnt lgkmcnt(0)
	v_mul_f32_e32 v96, v144, v12
	v_mul_f32_e32 v97, v145, v13
	v_mul_f32_e32 v98, v144, v54
	v_mul_f32_e32 v99, v145, v55
	v_mul_f32_e32 v100, v144, v58
	v_mul_f32_e32 v101, v145, v59
	v_mul_f32_e32 v172, v144, v62
	v_mul_f32_e32 v173, v145, v63
	v_fmac_f32_e32 v96, v146, v14
	v_fmac_f32_e32 v97, v147, v15
	v_fmac_f32_e32 v98, v146, v56
	v_fmac_f32_e32 v99, v147, v57
	v_fmac_f32_e32 v100, v146, v60
	v_fmac_f32_e32 v101, v147, v61
	v_fmac_f32_e32 v172, v146, v64
	v_fmac_f32_e32 v173, v147, v65
	ds_read_b128 v[0:3], v174 offset:5696
	ds_read_b128 v[4:7], v174 offset:5952
	ds_read_b128 v[8:11], v174 offset:6208
	ds_read_b128 v[12:15], v174 offset:6464
	ds_read_b128 v[16:19], v174 offset:6720
	ds_read_b128 v[20:23], v174 offset:6976
	ds_read_b128 v[24:27], v174 offset:7232
	ds_read_b128 v[28:31], v174 offset:7488
	ds_read_b128 v[32:35], v174 offset:7744
	ds_read_b128 v[36:39], v175 offset:8512
	ds_read_b32 v40, v163 offset:8000
	ds_read_b32 v41, v163 offset:8256
	v_mul_f32_e32 v148, v78, v94
	v_mul_f32_e32 v149, v79, v94
	v_mul_f32_e32 v150, v80, v94
	v_mul_f32_e32 v151, v81, v94
	v_add_f32_e32 v168, v96, v97
	v_add_f32_e32 v166, v98, v99
	v_add_f32_e32 v169, v100, v101
	v_add_f32_e32 v170, v172, v173
	v_fmac_f32_e32 v148, v86, v95
	v_fmac_f32_e32 v149, v87, v95
	v_fmac_f32_e32 v150, v88, v95
	v_fmac_f32_e32 v151, v89, v95
	v_add_f32_dpp v168, v168, v168 row_mirror row_mask:0xf bank_mask:0xf bound_ctrl:1
	v_add_f32_dpp v166, v166, v166 row_mirror row_mask:0xf bank_mask:0xf bound_ctrl:1
	v_add_f32_dpp v169, v169, v169 row_mirror row_mask:0xf bank_mask:0xf bound_ctrl:1
	v_add_f32_dpp v170, v170, v170 row_mirror row_mask:0xf bank_mask:0xf bound_ctrl:1
	v_add_f32_dpp v168, v168, v168 row_half_mirror row_mask:0xf bank_mask:0xf bound_ctrl:1
	v_add_f32_dpp v166, v166, v166 row_half_mirror row_mask:0xf bank_mask:0xf bound_ctrl:1
	v_add_f32_dpp v169, v169, v169 row_half_mirror row_mask:0xf bank_mask:0xf bound_ctrl:1
	v_add_f32_dpp v170, v170, v170 row_half_mirror row_mask:0xf bank_mask:0xf bound_ctrl:1
	v_add_f32_dpp v168, v168, v168 quad_perm:[1,0,3,2] row_mask:0xf bank_mask:0xf bound_ctrl:1
	v_add_f32_dpp v166, v166, v166 quad_perm:[1,0,3,2] row_mask:0xf bank_mask:0xf bound_ctrl:1
	v_add_f32_dpp v169, v169, v169 quad_perm:[1,0,3,2] row_mask:0xf bank_mask:0xf bound_ctrl:1
	v_add_f32_dpp v170, v170, v170 quad_perm:[1,0,3,2] row_mask:0xf bank_mask:0xf bound_ctrl:1
	v_add_f32_dpp v168, v168, v168 quad_perm:[2,3,0,1] row_mask:0xf bank_mask:0xf bound_ctrl:1
	v_add_f32_dpp v166, v166, v166 quad_perm:[2,3,0,1] row_mask:0xf bank_mask:0xf bound_ctrl:1
	v_add_f32_dpp v169, v169, v169 quad_perm:[2,3,0,1] row_mask:0xf bank_mask:0xf bound_ctrl:1
	v_add_f32_dpp v170, v170, v170 quad_perm:[2,3,0,1] row_mask:0xf bank_mask:0xf bound_ctrl:1
	v_fma_f32 v164, v94, v91, v169
	v_fma_f32 v171, v94, v93, v170
	v_fmac_f32_e32 v148, v74, v166
	v_fmac_f32_e32 v149, v75, v166
	v_fma_f32 v167, v166, v90, v164
	v_fmac_f32_e32 v150, v76, v166
	v_fmac_f32_e32 v151, v77, v166
	v_fma_f32 v171, v166, v92, v171
	v_cndmask_b32_e64 v162, v162, v168, s[48:49]
	v_fmac_f32_e32 v148, v82, v167
	v_fmac_f32_e32 v149, v83, v167
	v_fmac_f32_e32 v150, v84, v167
	v_fmac_f32_e32 v151, v85, v167
	v_cndmask_b32_e64 v162, v162, v171, s[50:51]
	v_fma_f32 v144, v144, v70, v148
	v_fma_f32 v145, v145, v71, v149
	v_fma_f32 v146, v146, v72, v150
	v_fma_f32 v147, v147, v73, v151
	s_waitcnt lgkmcnt(0)
	v_mul_f32_e32 v96, v144, v66
	v_mul_f32_e32 v97, v145, v67
	v_mul_f32_e32 v98, v144, v0
	v_mul_f32_e32 v99, v145, v1
	v_mul_f32_e32 v100, v144, v4
	v_mul_f32_e32 v101, v145, v5
	v_mul_f32_e32 v172, v144, v8
	v_mul_f32_e32 v173, v145, v9
	v_fmac_f32_e32 v96, v146, v68
	v_fmac_f32_e32 v97, v147, v69
	v_fmac_f32_e32 v98, v146, v2
	v_fmac_f32_e32 v99, v147, v3
	v_fmac_f32_e32 v100, v146, v6
	v_fmac_f32_e32 v101, v147, v7
	v_fmac_f32_e32 v172, v146, v10
	v_fmac_f32_e32 v173, v147, v11
	ds_read_b128 v[54:57], v174 offset:8544
	ds_read_b128 v[58:61], v174 offset:8800
	ds_read_b128 v[62:65], v174 offset:9056
	ds_read_b128 v[66:69], v174 offset:9312
	ds_read_b128 v[70:73], v174 offset:9568
	ds_read_b128 v[74:77], v174 offset:9824
	ds_read_b128 v[78:81], v174 offset:10080
	ds_read_b128 v[82:85], v174 offset:10336
	ds_read_b128 v[86:89], v174 offset:10592
	ds_read_b128 v[90:93], v175 offset:11360
	ds_read_b32 v94, v163 offset:10848
	ds_read_b32 v95, v163 offset:11104
	v_mul_f32_e32 v148, v24, v40
	v_mul_f32_e32 v149, v25, v40
	v_mul_f32_e32 v150, v26, v40
	v_mul_f32_e32 v151, v27, v40
	v_add_f32_e32 v168, v96, v97
	v_add_f32_e32 v166, v98, v99
	v_add_f32_e32 v169, v100, v101
	v_add_f32_e32 v170, v172, v173
	v_fmac_f32_e32 v148, v32, v41
	v_fmac_f32_e32 v149, v33, v41
	v_fmac_f32_e32 v150, v34, v41
	v_fmac_f32_e32 v151, v35, v41
	v_add_f32_dpp v168, v168, v168 row_mirror row_mask:0xf bank_mask:0xf bound_ctrl:1
	v_add_f32_dpp v166, v166, v166 row_mirror row_mask:0xf bank_mask:0xf bound_ctrl:1
	v_add_f32_dpp v169, v169, v169 row_mirror row_mask:0xf bank_mask:0xf bound_ctrl:1
	v_add_f32_dpp v170, v170, v170 row_mirror row_mask:0xf bank_mask:0xf bound_ctrl:1
	v_add_f32_dpp v168, v168, v168 row_half_mirror row_mask:0xf bank_mask:0xf bound_ctrl:1
	v_add_f32_dpp v166, v166, v166 row_half_mirror row_mask:0xf bank_mask:0xf bound_ctrl:1
	v_add_f32_dpp v169, v169, v169 row_half_mirror row_mask:0xf bank_mask:0xf bound_ctrl:1
	v_add_f32_dpp v170, v170, v170 row_half_mirror row_mask:0xf bank_mask:0xf bound_ctrl:1
	v_add_f32_dpp v168, v168, v168 quad_perm:[1,0,3,2] row_mask:0xf bank_mask:0xf bound_ctrl:1
	v_add_f32_dpp v166, v166, v166 quad_perm:[1,0,3,2] row_mask:0xf bank_mask:0xf bound_ctrl:1
	v_add_f32_dpp v169, v169, v169 quad_perm:[1,0,3,2] row_mask:0xf bank_mask:0xf bound_ctrl:1
	v_add_f32_dpp v170, v170, v170 quad_perm:[1,0,3,2] row_mask:0xf bank_mask:0xf bound_ctrl:1
	v_add_f32_dpp v168, v168, v168 quad_perm:[2,3,0,1] row_mask:0xf bank_mask:0xf bound_ctrl:1
	v_add_f32_dpp v166, v166, v166 quad_perm:[2,3,0,1] row_mask:0xf bank_mask:0xf bound_ctrl:1
	v_add_f32_dpp v169, v169, v169 quad_perm:[2,3,0,1] row_mask:0xf bank_mask:0xf bound_ctrl:1
	v_add_f32_dpp v170, v170, v170 quad_perm:[2,3,0,1] row_mask:0xf bank_mask:0xf bound_ctrl:1
	v_fma_f32 v164, v40, v37, v169
	v_fma_f32 v171, v40, v39, v170
	v_fmac_f32_e32 v148, v20, v166
	v_fmac_f32_e32 v149, v21, v166
	v_fma_f32 v167, v166, v36, v164
	v_fmac_f32_e32 v150, v22, v166
	v_fmac_f32_e32 v151, v23, v166
	v_fma_f32 v171, v166, v38, v171
	v_cndmask_b32_e64 v162, v162, v168, s[52:53]
	v_fmac_f32_e32 v148, v28, v167
	v_fmac_f32_e32 v149, v29, v167
	v_fmac_f32_e32 v150, v30, v167
	v_fmac_f32_e32 v151, v31, v167
	v_cndmask_b32_e64 v162, v162, v171, s[54:55]
	v_fma_f32 v144, v144, v16, v148
	v_fma_f32 v145, v145, v17, v149
	v_fma_f32 v146, v146, v18, v150
	v_fma_f32 v147, v147, v19, v151
	s_waitcnt lgkmcnt(0)
	v_mul_f32_e32 v96, v144, v12
	v_mul_f32_e32 v97, v145, v13
	v_mul_f32_e32 v98, v144, v54
	v_mul_f32_e32 v99, v145, v55
	v_mul_f32_e32 v100, v144, v58
	v_mul_f32_e32 v101, v145, v59
	v_mul_f32_e32 v172, v144, v62
	v_mul_f32_e32 v173, v145, v63
	v_fmac_f32_e32 v96, v146, v14
	v_fmac_f32_e32 v97, v147, v15
	v_fmac_f32_e32 v98, v146, v56
	v_fmac_f32_e32 v99, v147, v57
	v_fmac_f32_e32 v100, v146, v60
	v_fmac_f32_e32 v101, v147, v61
	v_fmac_f32_e32 v172, v146, v64
	v_fmac_f32_e32 v173, v147, v65
	ds_read_b128 v[0:3], v174 offset:11392
	ds_read_b128 v[4:7], v174 offset:11648
	ds_read_b128 v[8:11], v174 offset:11904
	ds_read_b128 v[12:15], v174 offset:12160
	ds_read_b128 v[16:19], v174 offset:12416
	ds_read_b128 v[20:23], v174 offset:12672
	ds_read_b128 v[24:27], v174 offset:12928
	ds_read_b128 v[28:31], v174 offset:13184
	ds_read_b128 v[32:35], v174 offset:13440
	ds_read_b128 v[36:39], v175 offset:14208
	ds_read_b32 v40, v163 offset:13696
	ds_read_b32 v41, v163 offset:13952
	v_mul_f32_e32 v148, v78, v94
	v_mul_f32_e32 v149, v79, v94
	v_mul_f32_e32 v150, v80, v94
	v_mul_f32_e32 v151, v81, v94
	v_add_f32_e32 v168, v96, v97
	v_add_f32_e32 v166, v98, v99
	v_add_f32_e32 v169, v100, v101
	v_add_f32_e32 v170, v172, v173
	v_fmac_f32_e32 v148, v86, v95
	v_fmac_f32_e32 v149, v87, v95
	v_fmac_f32_e32 v150, v88, v95
	v_fmac_f32_e32 v151, v89, v95
	v_add_f32_dpp v168, v168, v168 row_mirror row_mask:0xf bank_mask:0xf bound_ctrl:1
	v_add_f32_dpp v166, v166, v166 row_mirror row_mask:0xf bank_mask:0xf bound_ctrl:1
	v_add_f32_dpp v169, v169, v169 row_mirror row_mask:0xf bank_mask:0xf bound_ctrl:1
	v_add_f32_dpp v170, v170, v170 row_mirror row_mask:0xf bank_mask:0xf bound_ctrl:1
	v_add_f32_dpp v168, v168, v168 row_half_mirror row_mask:0xf bank_mask:0xf bound_ctrl:1
	v_add_f32_dpp v166, v166, v166 row_half_mirror row_mask:0xf bank_mask:0xf bound_ctrl:1
	v_add_f32_dpp v169, v169, v169 row_half_mirror row_mask:0xf bank_mask:0xf bound_ctrl:1
	v_add_f32_dpp v170, v170, v170 row_half_mirror row_mask:0xf bank_mask:0xf bound_ctrl:1
	v_add_f32_dpp v168, v168, v168 quad_perm:[1,0,3,2] row_mask:0xf bank_mask:0xf bound_ctrl:1
	v_add_f32_dpp v166, v166, v166 quad_perm:[1,0,3,2] row_mask:0xf bank_mask:0xf bound_ctrl:1
	v_add_f32_dpp v169, v169, v169 quad_perm:[1,0,3,2] row_mask:0xf bank_mask:0xf bound_ctrl:1
	v_add_f32_dpp v170, v170, v170 quad_perm:[1,0,3,2] row_mask:0xf bank_mask:0xf bound_ctrl:1
	v_add_f32_dpp v168, v168, v168 quad_perm:[2,3,0,1] row_mask:0xf bank_mask:0xf bound_ctrl:1
	v_add_f32_dpp v166, v166, v166 quad_perm:[2,3,0,1] row_mask:0xf bank_mask:0xf bound_ctrl:1
	v_add_f32_dpp v169, v169, v169 quad_perm:[2,3,0,1] row_mask:0xf bank_mask:0xf bound_ctrl:1
	v_add_f32_dpp v170, v170, v170 quad_perm:[2,3,0,1] row_mask:0xf bank_mask:0xf bound_ctrl:1
	v_fma_f32 v164, v94, v91, v169
	v_fma_f32 v171, v94, v93, v170
	v_fmac_f32_e32 v148, v74, v166
	v_fmac_f32_e32 v149, v75, v166
	v_fma_f32 v167, v166, v90, v164
	v_fmac_f32_e32 v150, v76, v166
	v_fmac_f32_e32 v151, v77, v166
	v_fma_f32 v171, v166, v92, v171
	v_cndmask_b32_e64 v162, v162, v168, s[56:57]
	v_fmac_f32_e32 v148, v82, v167
	v_fmac_f32_e32 v149, v83, v167
	v_fmac_f32_e32 v150, v84, v167
	v_fmac_f32_e32 v151, v85, v167
	v_cndmask_b32_e64 v162, v162, v171, s[58:59]
	v_fma_f32 v144, v144, v70, v148
	v_fma_f32 v145, v145, v71, v149
	v_fma_f32 v146, v146, v72, v150
	v_fma_f32 v147, v147, v73, v151
	s_waitcnt lgkmcnt(0)
	v_mul_f32_e32 v96, v144, v66
	v_mul_f32_e32 v97, v145, v67
	v_mul_f32_e32 v98, v144, v0
	v_mul_f32_e32 v99, v145, v1
	v_mul_f32_e32 v100, v144, v4
	v_mul_f32_e32 v101, v145, v5
	v_mul_f32_e32 v172, v144, v8
	v_mul_f32_e32 v173, v145, v9
	v_fmac_f32_e32 v96, v146, v68
	v_fmac_f32_e32 v97, v147, v69
	v_fmac_f32_e32 v98, v146, v2
	v_fmac_f32_e32 v99, v147, v3
	v_fmac_f32_e32 v100, v146, v6
	v_fmac_f32_e32 v101, v147, v7
	v_fmac_f32_e32 v172, v146, v10
	v_fmac_f32_e32 v173, v147, v11
	ds_read_b128 v[54:57], v174 offset:14240
	ds_read_b128 v[58:61], v174 offset:14496
	ds_read_b128 v[62:65], v174 offset:14752
	ds_read_b128 v[66:69], v174 offset:15008
	ds_read_b128 v[70:73], v174 offset:15264
	ds_read_b128 v[74:77], v174 offset:15520
	ds_read_b128 v[78:81], v174 offset:15776
	ds_read_b128 v[82:85], v174 offset:16032
	ds_read_b128 v[86:89], v174 offset:16288
	ds_read_b128 v[90:93], v175 offset:17056
	ds_read_b32 v94, v163 offset:16544
	ds_read_b32 v95, v163 offset:16800
	v_mul_f32_e32 v148, v24, v40
	v_mul_f32_e32 v149, v25, v40
	v_mul_f32_e32 v150, v26, v40
	v_mul_f32_e32 v151, v27, v40
	v_add_f32_e32 v168, v96, v97
	v_add_f32_e32 v166, v98, v99
	v_add_f32_e32 v169, v100, v101
	v_add_f32_e32 v170, v172, v173
	v_fmac_f32_e32 v148, v32, v41
	v_fmac_f32_e32 v149, v33, v41
	v_fmac_f32_e32 v150, v34, v41
	v_fmac_f32_e32 v151, v35, v41
	v_add_f32_dpp v168, v168, v168 row_mirror row_mask:0xf bank_mask:0xf bound_ctrl:1
	v_add_f32_dpp v166, v166, v166 row_mirror row_mask:0xf bank_mask:0xf bound_ctrl:1
	v_add_f32_dpp v169, v169, v169 row_mirror row_mask:0xf bank_mask:0xf bound_ctrl:1
	v_add_f32_dpp v170, v170, v170 row_mirror row_mask:0xf bank_mask:0xf bound_ctrl:1
	v_add_f32_dpp v168, v168, v168 row_half_mirror row_mask:0xf bank_mask:0xf bound_ctrl:1
	v_add_f32_dpp v166, v166, v166 row_half_mirror row_mask:0xf bank_mask:0xf bound_ctrl:1
	v_add_f32_dpp v169, v169, v169 row_half_mirror row_mask:0xf bank_mask:0xf bound_ctrl:1
	v_add_f32_dpp v170, v170, v170 row_half_mirror row_mask:0xf bank_mask:0xf bound_ctrl:1
	v_add_f32_dpp v168, v168, v168 quad_perm:[1,0,3,2] row_mask:0xf bank_mask:0xf bound_ctrl:1
	v_add_f32_dpp v166, v166, v166 quad_perm:[1,0,3,2] row_mask:0xf bank_mask:0xf bound_ctrl:1
	v_add_f32_dpp v169, v169, v169 quad_perm:[1,0,3,2] row_mask:0xf bank_mask:0xf bound_ctrl:1
	v_add_f32_dpp v170, v170, v170 quad_perm:[1,0,3,2] row_mask:0xf bank_mask:0xf bound_ctrl:1
	v_add_f32_dpp v168, v168, v168 quad_perm:[2,3,0,1] row_mask:0xf bank_mask:0xf bound_ctrl:1
	v_add_f32_dpp v166, v166, v166 quad_perm:[2,3,0,1] row_mask:0xf bank_mask:0xf bound_ctrl:1
	v_add_f32_dpp v169, v169, v169 quad_perm:[2,3,0,1] row_mask:0xf bank_mask:0xf bound_ctrl:1
	v_add_f32_dpp v170, v170, v170 quad_perm:[2,3,0,1] row_mask:0xf bank_mask:0xf bound_ctrl:1
	v_fma_f32 v164, v40, v37, v169
	v_fma_f32 v171, v40, v39, v170
	v_fmac_f32_e32 v148, v20, v166
	v_fmac_f32_e32 v149, v21, v166
	v_fma_f32 v167, v166, v36, v164
	v_fmac_f32_e32 v150, v22, v166
	v_fmac_f32_e32 v151, v23, v166
	v_fma_f32 v171, v166, v38, v171
	v_cndmask_b32_e64 v162, v162, v168, s[60:61]
	v_fmac_f32_e32 v148, v28, v167
	v_fmac_f32_e32 v149, v29, v167
	v_fmac_f32_e32 v150, v30, v167
	v_fmac_f32_e32 v151, v31, v167
	v_cndmask_b32_e64 v162, v162, v171, s[62:63]
	v_fma_f32 v144, v144, v16, v148
	v_fma_f32 v145, v145, v17, v149
	v_fma_f32 v146, v146, v18, v150
	v_fma_f32 v147, v147, v19, v151
	s_waitcnt lgkmcnt(0)
	v_mul_f32_e32 v96, v144, v12
	v_mul_f32_e32 v97, v145, v13
	v_mul_f32_e32 v98, v144, v54
	v_mul_f32_e32 v99, v145, v55
	v_mul_f32_e32 v100, v144, v58
	v_mul_f32_e32 v101, v145, v59
	v_mul_f32_e32 v172, v144, v62
	v_mul_f32_e32 v173, v145, v63
	v_fmac_f32_e32 v96, v146, v14
	v_fmac_f32_e32 v97, v147, v15
	v_fmac_f32_e32 v98, v146, v56
	v_fmac_f32_e32 v99, v147, v57
	v_fmac_f32_e32 v100, v146, v60
	v_fmac_f32_e32 v101, v147, v61
	v_fmac_f32_e32 v172, v146, v64
	v_fmac_f32_e32 v173, v147, v65
	ds_read_b128 v[0:3], v174 offset:17088
	ds_read_b128 v[4:7], v174 offset:17344
	ds_read_b128 v[8:11], v174 offset:17600
	ds_read_b128 v[12:15], v174 offset:17856
	ds_read_b128 v[16:19], v174 offset:18112
	ds_read_b128 v[20:23], v174 offset:18368
	ds_read_b128 v[24:27], v174 offset:18624
	ds_read_b128 v[28:31], v174 offset:18880
	ds_read_b128 v[32:35], v174 offset:19136
	ds_read_b128 v[36:39], v175 offset:19904
	ds_read_b32 v40, v163 offset:19392
	ds_read_b32 v41, v163 offset:19648
	v_mul_f32_e32 v148, v78, v94
	v_mul_f32_e32 v149, v79, v94
	v_mul_f32_e32 v150, v80, v94
	v_mul_f32_e32 v151, v81, v94
	v_add_f32_e32 v168, v96, v97
	v_add_f32_e32 v166, v98, v99
	v_add_f32_e32 v169, v100, v101
	v_add_f32_e32 v170, v172, v173
	v_fmac_f32_e32 v148, v86, v95
	v_fmac_f32_e32 v149, v87, v95
	v_fmac_f32_e32 v150, v88, v95
	v_fmac_f32_e32 v151, v89, v95
	v_add_f32_dpp v168, v168, v168 row_mirror row_mask:0xf bank_mask:0xf bound_ctrl:1
	v_add_f32_dpp v166, v166, v166 row_mirror row_mask:0xf bank_mask:0xf bound_ctrl:1
	v_add_f32_dpp v169, v169, v169 row_mirror row_mask:0xf bank_mask:0xf bound_ctrl:1
	v_add_f32_dpp v170, v170, v170 row_mirror row_mask:0xf bank_mask:0xf bound_ctrl:1
	v_add_f32_dpp v168, v168, v168 row_half_mirror row_mask:0xf bank_mask:0xf bound_ctrl:1
	v_add_f32_dpp v166, v166, v166 row_half_mirror row_mask:0xf bank_mask:0xf bound_ctrl:1
	v_add_f32_dpp v169, v169, v169 row_half_mirror row_mask:0xf bank_mask:0xf bound_ctrl:1
	v_add_f32_dpp v170, v170, v170 row_half_mirror row_mask:0xf bank_mask:0xf bound_ctrl:1
	v_add_f32_dpp v168, v168, v168 quad_perm:[1,0,3,2] row_mask:0xf bank_mask:0xf bound_ctrl:1
	v_add_f32_dpp v166, v166, v166 quad_perm:[1,0,3,2] row_mask:0xf bank_mask:0xf bound_ctrl:1
	v_add_f32_dpp v169, v169, v169 quad_perm:[1,0,3,2] row_mask:0xf bank_mask:0xf bound_ctrl:1
	v_add_f32_dpp v170, v170, v170 quad_perm:[1,0,3,2] row_mask:0xf bank_mask:0xf bound_ctrl:1
	v_add_f32_dpp v168, v168, v168 quad_perm:[2,3,0,1] row_mask:0xf bank_mask:0xf bound_ctrl:1
	v_add_f32_dpp v166, v166, v166 quad_perm:[2,3,0,1] row_mask:0xf bank_mask:0xf bound_ctrl:1
	v_add_f32_dpp v169, v169, v169 quad_perm:[2,3,0,1] row_mask:0xf bank_mask:0xf bound_ctrl:1
	v_add_f32_dpp v170, v170, v170 quad_perm:[2,3,0,1] row_mask:0xf bank_mask:0xf bound_ctrl:1
	v_fma_f32 v164, v94, v91, v169
	v_fma_f32 v171, v94, v93, v170
	v_fmac_f32_e32 v148, v74, v166
	v_fmac_f32_e32 v149, v75, v166
	v_fma_f32 v167, v166, v90, v164
	v_fmac_f32_e32 v150, v76, v166
	v_fmac_f32_e32 v151, v77, v166
	v_fma_f32 v171, v166, v92, v171
	v_cndmask_b32_e64 v162, v162, v168, s[64:65]
	v_fmac_f32_e32 v148, v82, v167
	v_fmac_f32_e32 v149, v83, v167
	v_fmac_f32_e32 v150, v84, v167
	v_fmac_f32_e32 v151, v85, v167
	v_cndmask_b32_e64 v162, v162, v171, s[66:67]
	v_fma_f32 v144, v144, v70, v148
	v_fma_f32 v145, v145, v71, v149
	v_fma_f32 v146, v146, v72, v150
	v_fma_f32 v147, v147, v73, v151
	s_waitcnt lgkmcnt(0)
	v_mul_f32_e32 v96, v144, v66
	v_mul_f32_e32 v97, v145, v67
	v_mul_f32_e32 v98, v144, v0
	v_mul_f32_e32 v99, v145, v1
	v_mul_f32_e32 v100, v144, v4
	v_mul_f32_e32 v101, v145, v5
	v_mul_f32_e32 v172, v144, v8
	v_mul_f32_e32 v173, v145, v9
	v_fmac_f32_e32 v96, v146, v68
	v_fmac_f32_e32 v97, v147, v69
	v_fmac_f32_e32 v98, v146, v2
	v_fmac_f32_e32 v99, v147, v3
	v_fmac_f32_e32 v100, v146, v6
	v_fmac_f32_e32 v101, v147, v7
	v_fmac_f32_e32 v172, v146, v10
	v_fmac_f32_e32 v173, v147, v11
	ds_read_b128 v[54:57], v174 offset:19936
	ds_read_b128 v[58:61], v174 offset:20192
	ds_read_b128 v[62:65], v174 offset:20448
	ds_read_b128 v[66:69], v174 offset:20704
	ds_read_b128 v[70:73], v174 offset:20960
	ds_read_b128 v[74:77], v174 offset:21216
	ds_read_b128 v[78:81], v174 offset:21472
	ds_read_b128 v[82:85], v174 offset:21728
	ds_read_b128 v[86:89], v174 offset:21984
	ds_read_b128 v[90:93], v175 offset:22752
	ds_read_b32 v94, v163 offset:22240
	ds_read_b32 v95, v163 offset:22496
	v_mul_f32_e32 v148, v24, v40
	v_mul_f32_e32 v149, v25, v40
	v_mul_f32_e32 v150, v26, v40
	v_mul_f32_e32 v151, v27, v40
	v_add_f32_e32 v168, v96, v97
	v_add_f32_e32 v166, v98, v99
	v_add_f32_e32 v169, v100, v101
	v_add_f32_e32 v170, v172, v173
	v_fmac_f32_e32 v148, v32, v41
	v_fmac_f32_e32 v149, v33, v41
	v_fmac_f32_e32 v150, v34, v41
	v_fmac_f32_e32 v151, v35, v41
	v_add_f32_dpp v168, v168, v168 row_mirror row_mask:0xf bank_mask:0xf bound_ctrl:1
	v_add_f32_dpp v166, v166, v166 row_mirror row_mask:0xf bank_mask:0xf bound_ctrl:1
	v_add_f32_dpp v169, v169, v169 row_mirror row_mask:0xf bank_mask:0xf bound_ctrl:1
	v_add_f32_dpp v170, v170, v170 row_mirror row_mask:0xf bank_mask:0xf bound_ctrl:1
	v_add_f32_dpp v168, v168, v168 row_half_mirror row_mask:0xf bank_mask:0xf bound_ctrl:1
	v_add_f32_dpp v166, v166, v166 row_half_mirror row_mask:0xf bank_mask:0xf bound_ctrl:1
	v_add_f32_dpp v169, v169, v169 row_half_mirror row_mask:0xf bank_mask:0xf bound_ctrl:1
	v_add_f32_dpp v170, v170, v170 row_half_mirror row_mask:0xf bank_mask:0xf bound_ctrl:1
	v_add_f32_dpp v168, v168, v168 quad_perm:[1,0,3,2] row_mask:0xf bank_mask:0xf bound_ctrl:1
	v_add_f32_dpp v166, v166, v166 quad_perm:[1,0,3,2] row_mask:0xf bank_mask:0xf bound_ctrl:1
	v_add_f32_dpp v169, v169, v169 quad_perm:[1,0,3,2] row_mask:0xf bank_mask:0xf bound_ctrl:1
	v_add_f32_dpp v170, v170, v170 quad_perm:[1,0,3,2] row_mask:0xf bank_mask:0xf bound_ctrl:1
	v_add_f32_dpp v168, v168, v168 quad_perm:[2,3,0,1] row_mask:0xf bank_mask:0xf bound_ctrl:1
	v_add_f32_dpp v166, v166, v166 quad_perm:[2,3,0,1] row_mask:0xf bank_mask:0xf bound_ctrl:1
	v_add_f32_dpp v169, v169, v169 quad_perm:[2,3,0,1] row_mask:0xf bank_mask:0xf bound_ctrl:1
	v_add_f32_dpp v170, v170, v170 quad_perm:[2,3,0,1] row_mask:0xf bank_mask:0xf bound_ctrl:1
	v_fma_f32 v164, v40, v37, v169
	v_fma_f32 v171, v40, v39, v170
	v_fmac_f32_e32 v148, v20, v166
	v_fmac_f32_e32 v149, v21, v166
	v_fma_f32 v167, v166, v36, v164
	v_fmac_f32_e32 v150, v22, v166
	v_fmac_f32_e32 v151, v23, v166
	v_fma_f32 v171, v166, v38, v171
	v_cndmask_b32_e64 v162, v162, v168, s[68:69]
	v_fmac_f32_e32 v148, v28, v167
	v_fmac_f32_e32 v149, v29, v167
	v_fmac_f32_e32 v150, v30, v167
	v_fmac_f32_e32 v151, v31, v167
	v_cndmask_b32_e64 v162, v162, v171, s[70:71]
	v_fma_f32 v144, v144, v16, v148
	v_fma_f32 v145, v145, v17, v149
	v_fma_f32 v146, v146, v18, v150
	v_fma_f32 v147, v147, v19, v151
	s_waitcnt lgkmcnt(0)
	v_mul_f32_e32 v96, v144, v12
	v_mul_f32_e32 v97, v145, v13
	v_mul_f32_e32 v98, v144, v54
	v_mul_f32_e32 v99, v145, v55
	v_mul_f32_e32 v100, v144, v58
	v_mul_f32_e32 v101, v145, v59
	v_mul_f32_e32 v172, v144, v62
	v_mul_f32_e32 v173, v145, v63
	v_fmac_f32_e32 v96, v146, v14
	v_fmac_f32_e32 v97, v147, v15
	v_fmac_f32_e32 v98, v146, v56
	v_fmac_f32_e32 v99, v147, v57
	v_fmac_f32_e32 v100, v146, v60
	v_fmac_f32_e32 v101, v147, v61
	v_fmac_f32_e32 v172, v146, v64
	v_fmac_f32_e32 v173, v147, v65
	ds_read_b128 v[0:3], v174 offset:22784
	ds_read_b128 v[4:7], v174 offset:23040
	ds_read_b128 v[8:11], v174 offset:23296
	ds_read_b128 v[12:15], v174 offset:23552
	ds_read_b128 v[16:19], v174 offset:23808
	ds_read_b128 v[20:23], v174 offset:24064
	ds_read_b128 v[24:27], v174 offset:24320
	ds_read_b128 v[28:31], v174 offset:24576
	ds_read_b128 v[32:35], v174 offset:24832
	ds_read_b128 v[36:39], v175 offset:25600
	ds_read_b32 v40, v163 offset:25088
	ds_read_b32 v41, v163 offset:25344
	v_mul_f32_e32 v148, v78, v94
	v_mul_f32_e32 v149, v79, v94
	v_mul_f32_e32 v150, v80, v94
	v_mul_f32_e32 v151, v81, v94
	v_add_f32_e32 v168, v96, v97
	v_add_f32_e32 v166, v98, v99
	v_add_f32_e32 v169, v100, v101
	v_add_f32_e32 v170, v172, v173
	v_fmac_f32_e32 v148, v86, v95
	v_fmac_f32_e32 v149, v87, v95
	v_fmac_f32_e32 v150, v88, v95
	v_fmac_f32_e32 v151, v89, v95
	v_add_f32_dpp v168, v168, v168 row_mirror row_mask:0xf bank_mask:0xf bound_ctrl:1
	v_add_f32_dpp v166, v166, v166 row_mirror row_mask:0xf bank_mask:0xf bound_ctrl:1
	v_add_f32_dpp v169, v169, v169 row_mirror row_mask:0xf bank_mask:0xf bound_ctrl:1
	v_add_f32_dpp v170, v170, v170 row_mirror row_mask:0xf bank_mask:0xf bound_ctrl:1
	v_add_f32_dpp v168, v168, v168 row_half_mirror row_mask:0xf bank_mask:0xf bound_ctrl:1
	v_add_f32_dpp v166, v166, v166 row_half_mirror row_mask:0xf bank_mask:0xf bound_ctrl:1
	v_add_f32_dpp v169, v169, v169 row_half_mirror row_mask:0xf bank_mask:0xf bound_ctrl:1
	v_add_f32_dpp v170, v170, v170 row_half_mirror row_mask:0xf bank_mask:0xf bound_ctrl:1
	v_add_f32_dpp v168, v168, v168 quad_perm:[1,0,3,2] row_mask:0xf bank_mask:0xf bound_ctrl:1
	v_add_f32_dpp v166, v166, v166 quad_perm:[1,0,3,2] row_mask:0xf bank_mask:0xf bound_ctrl:1
	v_add_f32_dpp v169, v169, v169 quad_perm:[1,0,3,2] row_mask:0xf bank_mask:0xf bound_ctrl:1
	v_add_f32_dpp v170, v170, v170 quad_perm:[1,0,3,2] row_mask:0xf bank_mask:0xf bound_ctrl:1
	v_add_f32_dpp v168, v168, v168 quad_perm:[2,3,0,1] row_mask:0xf bank_mask:0xf bound_ctrl:1
	v_add_f32_dpp v166, v166, v166 quad_perm:[2,3,0,1] row_mask:0xf bank_mask:0xf bound_ctrl:1
	v_add_f32_dpp v169, v169, v169 quad_perm:[2,3,0,1] row_mask:0xf bank_mask:0xf bound_ctrl:1
	v_add_f32_dpp v170, v170, v170 quad_perm:[2,3,0,1] row_mask:0xf bank_mask:0xf bound_ctrl:1
	v_fma_f32 v164, v94, v91, v169
	v_fma_f32 v171, v94, v93, v170
	v_fmac_f32_e32 v148, v74, v166
	v_fmac_f32_e32 v149, v75, v166
	v_fma_f32 v167, v166, v90, v164
	v_fmac_f32_e32 v150, v76, v166
	v_fmac_f32_e32 v151, v77, v166
	v_fma_f32 v171, v166, v92, v171
	v_cndmask_b32_e64 v162, v162, v168, s[44:45]
	v_fmac_f32_e32 v148, v82, v167
	v_fmac_f32_e32 v149, v83, v167
	v_fmac_f32_e32 v150, v84, v167
	v_fmac_f32_e32 v151, v85, v167
	v_cndmask_b32_e64 v162, v162, v171, s[42:43]
	v_fma_f32 v144, v144, v70, v148
	v_fma_f32 v145, v145, v71, v149
	v_fma_f32 v146, v146, v72, v150
	v_fma_f32 v147, v147, v73, v151
	s_waitcnt lgkmcnt(0)
	v_mul_f32_e32 v96, v144, v66
	v_mul_f32_e32 v97, v145, v67
	v_mul_f32_e32 v98, v144, v0
	v_mul_f32_e32 v99, v145, v1
	v_mul_f32_e32 v100, v144, v4
	v_mul_f32_e32 v101, v145, v5
	v_mul_f32_e32 v172, v144, v8
	v_mul_f32_e32 v173, v145, v9
	v_fmac_f32_e32 v96, v146, v68
	v_fmac_f32_e32 v97, v147, v69
	v_fmac_f32_e32 v98, v146, v2
	v_fmac_f32_e32 v99, v147, v3
	v_fmac_f32_e32 v100, v146, v6
	v_fmac_f32_e32 v101, v147, v7
	v_fmac_f32_e32 v172, v146, v10
	v_fmac_f32_e32 v173, v147, v11
	ds_read_b128 v[54:57], v174 offset:25632
	ds_read_b128 v[58:61], v174 offset:25888
	ds_read_b128 v[62:65], v174 offset:26144
	ds_read_b128 v[66:69], v174 offset:26400
	ds_read_b128 v[70:73], v174 offset:26656
	ds_read_b128 v[74:77], v174 offset:26912
	ds_read_b128 v[78:81], v174 offset:27168
	ds_read_b128 v[82:85], v174 offset:27424
	ds_read_b128 v[86:89], v174 offset:27680
	ds_read_b128 v[90:93], v175 offset:28448
	ds_read_b32 v94, v163 offset:27936
	ds_read_b32 v95, v163 offset:28192
	v_mul_f32_e32 v148, v24, v40
	v_mul_f32_e32 v149, v25, v40
	v_mul_f32_e32 v150, v26, v40
	v_mul_f32_e32 v151, v27, v40
	v_add_f32_e32 v168, v96, v97
	v_add_f32_e32 v166, v98, v99
	v_add_f32_e32 v169, v100, v101
	v_add_f32_e32 v170, v172, v173
	v_fmac_f32_e32 v148, v32, v41
	v_fmac_f32_e32 v149, v33, v41
	v_fmac_f32_e32 v150, v34, v41
	v_fmac_f32_e32 v151, v35, v41
	v_add_f32_dpp v168, v168, v168 row_mirror row_mask:0xf bank_mask:0xf bound_ctrl:1
	v_add_f32_dpp v166, v166, v166 row_mirror row_mask:0xf bank_mask:0xf bound_ctrl:1
	v_add_f32_dpp v169, v169, v169 row_mirror row_mask:0xf bank_mask:0xf bound_ctrl:1
	v_add_f32_dpp v170, v170, v170 row_mirror row_mask:0xf bank_mask:0xf bound_ctrl:1
	v_add_f32_dpp v168, v168, v168 row_half_mirror row_mask:0xf bank_mask:0xf bound_ctrl:1
	v_add_f32_dpp v166, v166, v166 row_half_mirror row_mask:0xf bank_mask:0xf bound_ctrl:1
	v_add_f32_dpp v169, v169, v169 row_half_mirror row_mask:0xf bank_mask:0xf bound_ctrl:1
	v_add_f32_dpp v170, v170, v170 row_half_mirror row_mask:0xf bank_mask:0xf bound_ctrl:1
	v_add_f32_dpp v168, v168, v168 quad_perm:[1,0,3,2] row_mask:0xf bank_mask:0xf bound_ctrl:1
	v_add_f32_dpp v166, v166, v166 quad_perm:[1,0,3,2] row_mask:0xf bank_mask:0xf bound_ctrl:1
	v_add_f32_dpp v169, v169, v169 quad_perm:[1,0,3,2] row_mask:0xf bank_mask:0xf bound_ctrl:1
	v_add_f32_dpp v170, v170, v170 quad_perm:[1,0,3,2] row_mask:0xf bank_mask:0xf bound_ctrl:1
	v_add_f32_dpp v168, v168, v168 quad_perm:[2,3,0,1] row_mask:0xf bank_mask:0xf bound_ctrl:1
	v_add_f32_dpp v166, v166, v166 quad_perm:[2,3,0,1] row_mask:0xf bank_mask:0xf bound_ctrl:1
	v_add_f32_dpp v169, v169, v169 quad_perm:[2,3,0,1] row_mask:0xf bank_mask:0xf bound_ctrl:1
	v_add_f32_dpp v170, v170, v170 quad_perm:[2,3,0,1] row_mask:0xf bank_mask:0xf bound_ctrl:1
	v_fma_f32 v164, v40, v37, v169
	v_fma_f32 v171, v40, v39, v170
	v_fmac_f32_e32 v148, v20, v166
	v_fmac_f32_e32 v149, v21, v166
	v_fma_f32 v167, v166, v36, v164
	v_fmac_f32_e32 v150, v22, v166
	v_fmac_f32_e32 v151, v23, v166
	v_fma_f32 v171, v166, v38, v171
	v_cndmask_b32_e64 v162, v162, v168, s[46:47]
	s_lshl_b32 s6, s9, 1
	s_add_i32 s6, s6, 1
	s_add_i32 s6, s6, -1
	s_and_b32 s6, s6, 7
	s_lshl_b32 s6, s6, 10
	v_add_u32_e32 v161, s6, v156
	ds_write_b32 v161, v162
	v_fmac_f32_e32 v148, v28, v167
	v_fmac_f32_e32 v149, v29, v167
	v_fmac_f32_e32 v150, v30, v167
	v_fmac_f32_e32 v151, v31, v167
	v_cndmask_b32_e64 v162, v162, v171, s[38:39]
	v_fma_f32 v144, v144, v16, v148
	v_fma_f32 v145, v145, v17, v149
	v_fma_f32 v146, v146, v18, v150
	v_fma_f32 v147, v147, v19, v151
	s_waitcnt lgkmcnt(0)
	v_mul_f32_e32 v96, v144, v12
	v_mul_f32_e32 v97, v145, v13
	v_mul_f32_e32 v98, v144, v54
	v_mul_f32_e32 v99, v145, v55
	v_mul_f32_e32 v100, v144, v58
	v_mul_f32_e32 v101, v145, v59
	v_mul_f32_e32 v172, v144, v62
	v_mul_f32_e32 v173, v145, v63
	v_fmac_f32_e32 v96, v146, v14
	v_fmac_f32_e32 v97, v147, v15
	v_fmac_f32_e32 v98, v146, v56
	v_fmac_f32_e32 v99, v147, v57
	v_fmac_f32_e32 v100, v146, v60
	v_fmac_f32_e32 v101, v147, v61
	v_fmac_f32_e32 v172, v146, v64
	v_fmac_f32_e32 v173, v147, v65
	ds_read_b128 v[0:3], v174 offset:28480
	ds_read_b128 v[4:7], v174 offset:28736
	ds_read_b128 v[8:11], v174 offset:28992
	ds_read_b128 v[12:15], v174 offset:29248
	ds_read_b128 v[16:19], v174 offset:29504
	ds_read_b128 v[20:23], v174 offset:29760
	ds_read_b128 v[24:27], v174 offset:30016
	ds_read_b128 v[28:31], v174 offset:30272
	ds_read_b128 v[32:35], v174 offset:30528
	ds_read_b128 v[36:39], v175 offset:31296
	ds_read_b32 v40, v163 offset:30784
	ds_read_b32 v41, v163 offset:31040
	v_mul_f32_e32 v148, v78, v94
	v_mul_f32_e32 v149, v79, v94
	v_mul_f32_e32 v150, v80, v94
	v_mul_f32_e32 v151, v81, v94
	v_add_f32_e32 v168, v96, v97
	v_add_f32_e32 v166, v98, v99
	v_add_f32_e32 v169, v100, v101
	v_add_f32_e32 v170, v172, v173
	v_fmac_f32_e32 v148, v86, v95
	v_fmac_f32_e32 v149, v87, v95
	v_fmac_f32_e32 v150, v88, v95
	v_fmac_f32_e32 v151, v89, v95
	v_add_f32_dpp v168, v168, v168 row_mirror row_mask:0xf bank_mask:0xf bound_ctrl:1
	v_add_f32_dpp v166, v166, v166 row_mirror row_mask:0xf bank_mask:0xf bound_ctrl:1
	v_add_f32_dpp v169, v169, v169 row_mirror row_mask:0xf bank_mask:0xf bound_ctrl:1
	v_add_f32_dpp v170, v170, v170 row_mirror row_mask:0xf bank_mask:0xf bound_ctrl:1
	v_add_f32_dpp v168, v168, v168 row_half_mirror row_mask:0xf bank_mask:0xf bound_ctrl:1
	v_add_f32_dpp v166, v166, v166 row_half_mirror row_mask:0xf bank_mask:0xf bound_ctrl:1
	v_add_f32_dpp v169, v169, v169 row_half_mirror row_mask:0xf bank_mask:0xf bound_ctrl:1
	v_add_f32_dpp v170, v170, v170 row_half_mirror row_mask:0xf bank_mask:0xf bound_ctrl:1
	v_add_f32_dpp v168, v168, v168 quad_perm:[1,0,3,2] row_mask:0xf bank_mask:0xf bound_ctrl:1
	v_add_f32_dpp v166, v166, v166 quad_perm:[1,0,3,2] row_mask:0xf bank_mask:0xf bound_ctrl:1
	v_add_f32_dpp v169, v169, v169 quad_perm:[1,0,3,2] row_mask:0xf bank_mask:0xf bound_ctrl:1
	v_add_f32_dpp v170, v170, v170 quad_perm:[1,0,3,2] row_mask:0xf bank_mask:0xf bound_ctrl:1
	v_add_f32_dpp v168, v168, v168 quad_perm:[2,3,0,1] row_mask:0xf bank_mask:0xf bound_ctrl:1
	v_add_f32_dpp v166, v166, v166 quad_perm:[2,3,0,1] row_mask:0xf bank_mask:0xf bound_ctrl:1
	v_add_f32_dpp v169, v169, v169 quad_perm:[2,3,0,1] row_mask:0xf bank_mask:0xf bound_ctrl:1
	v_add_f32_dpp v170, v170, v170 quad_perm:[2,3,0,1] row_mask:0xf bank_mask:0xf bound_ctrl:1
	v_fma_f32 v164, v94, v91, v169
	v_fma_f32 v171, v94, v93, v170
	v_fmac_f32_e32 v148, v74, v166
	v_fmac_f32_e32 v149, v75, v166
	v_fma_f32 v167, v166, v90, v164
	v_fmac_f32_e32 v150, v76, v166
	v_fmac_f32_e32 v151, v77, v166
	v_fma_f32 v171, v166, v92, v171
	v_cndmask_b32_e64 v162, v162, v168, s[48:49]
	v_fmac_f32_e32 v148, v82, v167
	v_fmac_f32_e32 v149, v83, v167
	v_fmac_f32_e32 v150, v84, v167
	v_fmac_f32_e32 v151, v85, v167
	v_cndmask_b32_e64 v162, v162, v171, s[50:51]
	v_fma_f32 v144, v144, v70, v148
	v_fma_f32 v145, v145, v71, v149
	v_fma_f32 v146, v146, v72, v150
	v_fma_f32 v147, v147, v73, v151
	s_waitcnt lgkmcnt(0)
	v_mul_f32_e32 v96, v144, v66
	v_mul_f32_e32 v97, v145, v67
	v_mul_f32_e32 v98, v144, v0
	v_mul_f32_e32 v99, v145, v1
	v_mul_f32_e32 v100, v144, v4
	v_mul_f32_e32 v101, v145, v5
	v_mul_f32_e32 v172, v144, v8
	v_mul_f32_e32 v173, v145, v9
	v_fmac_f32_e32 v96, v146, v68
	v_fmac_f32_e32 v97, v147, v69
	v_fmac_f32_e32 v98, v146, v2
	v_fmac_f32_e32 v99, v147, v3
	v_fmac_f32_e32 v100, v146, v6
	v_fmac_f32_e32 v101, v147, v7
	v_fmac_f32_e32 v172, v146, v10
	v_fmac_f32_e32 v173, v147, v11
	ds_read_b128 v[54:57], v174 offset:31328
	ds_read_b128 v[58:61], v174 offset:31584
	ds_read_b128 v[62:65], v174 offset:31840
	ds_read_b128 v[66:69], v174 offset:32096
	ds_read_b128 v[70:73], v174 offset:32352
	ds_read_b128 v[74:77], v174 offset:32608
	ds_read_b128 v[78:81], v174 offset:32864
	ds_read_b128 v[82:85], v174 offset:33120
	ds_read_b128 v[86:89], v174 offset:33376
	ds_read_b128 v[90:93], v175 offset:34144
	ds_read_b32 v94, v163 offset:33632
	ds_read_b32 v95, v163 offset:33888
	v_mul_f32_e32 v148, v24, v40
	v_mul_f32_e32 v149, v25, v40
	v_mul_f32_e32 v150, v26, v40
	v_mul_f32_e32 v151, v27, v40
	v_add_f32_e32 v168, v96, v97
	v_add_f32_e32 v166, v98, v99
	v_add_f32_e32 v169, v100, v101
	v_add_f32_e32 v170, v172, v173
	v_fmac_f32_e32 v148, v32, v41
	v_fmac_f32_e32 v149, v33, v41
	v_fmac_f32_e32 v150, v34, v41
	v_fmac_f32_e32 v151, v35, v41
	v_add_f32_dpp v168, v168, v168 row_mirror row_mask:0xf bank_mask:0xf bound_ctrl:1
	v_add_f32_dpp v166, v166, v166 row_mirror row_mask:0xf bank_mask:0xf bound_ctrl:1
	v_add_f32_dpp v169, v169, v169 row_mirror row_mask:0xf bank_mask:0xf bound_ctrl:1
	v_add_f32_dpp v170, v170, v170 row_mirror row_mask:0xf bank_mask:0xf bound_ctrl:1
	v_add_f32_dpp v168, v168, v168 row_half_mirror row_mask:0xf bank_mask:0xf bound_ctrl:1
	v_add_f32_dpp v166, v166, v166 row_half_mirror row_mask:0xf bank_mask:0xf bound_ctrl:1
	v_add_f32_dpp v169, v169, v169 row_half_mirror row_mask:0xf bank_mask:0xf bound_ctrl:1
	v_add_f32_dpp v170, v170, v170 row_half_mirror row_mask:0xf bank_mask:0xf bound_ctrl:1
	v_add_f32_dpp v168, v168, v168 quad_perm:[1,0,3,2] row_mask:0xf bank_mask:0xf bound_ctrl:1
	v_add_f32_dpp v166, v166, v166 quad_perm:[1,0,3,2] row_mask:0xf bank_mask:0xf bound_ctrl:1
	v_add_f32_dpp v169, v169, v169 quad_perm:[1,0,3,2] row_mask:0xf bank_mask:0xf bound_ctrl:1
	v_add_f32_dpp v170, v170, v170 quad_perm:[1,0,3,2] row_mask:0xf bank_mask:0xf bound_ctrl:1
	v_add_f32_dpp v168, v168, v168 quad_perm:[2,3,0,1] row_mask:0xf bank_mask:0xf bound_ctrl:1
	v_add_f32_dpp v166, v166, v166 quad_perm:[2,3,0,1] row_mask:0xf bank_mask:0xf bound_ctrl:1
	v_add_f32_dpp v169, v169, v169 quad_perm:[2,3,0,1] row_mask:0xf bank_mask:0xf bound_ctrl:1
	v_add_f32_dpp v170, v170, v170 quad_perm:[2,3,0,1] row_mask:0xf bank_mask:0xf bound_ctrl:1
	v_fma_f32 v164, v40, v37, v169
	v_fma_f32 v171, v40, v39, v170
	v_fmac_f32_e32 v148, v20, v166
	v_fmac_f32_e32 v149, v21, v166
	v_fma_f32 v167, v166, v36, v164
	v_fmac_f32_e32 v150, v22, v166
	v_fmac_f32_e32 v151, v23, v166
	v_fma_f32 v171, v166, v38, v171
	v_cndmask_b32_e64 v162, v162, v168, s[52:53]
	v_fmac_f32_e32 v148, v28, v167
	v_fmac_f32_e32 v149, v29, v167
	v_fmac_f32_e32 v150, v30, v167
	v_fmac_f32_e32 v151, v31, v167
	v_cndmask_b32_e64 v162, v162, v171, s[54:55]
	v_fma_f32 v144, v144, v16, v148
	v_fma_f32 v145, v145, v17, v149
	v_fma_f32 v146, v146, v18, v150
	v_fma_f32 v147, v147, v19, v151
	s_waitcnt lgkmcnt(0)
	v_mul_f32_e32 v96, v144, v12
	v_mul_f32_e32 v97, v145, v13
	v_mul_f32_e32 v98, v144, v54
	v_mul_f32_e32 v99, v145, v55
	v_mul_f32_e32 v100, v144, v58
	v_mul_f32_e32 v101, v145, v59
	v_mul_f32_e32 v172, v144, v62
	v_mul_f32_e32 v173, v145, v63
	v_fmac_f32_e32 v96, v146, v14
	v_fmac_f32_e32 v97, v147, v15
	v_fmac_f32_e32 v98, v146, v56
	v_fmac_f32_e32 v99, v147, v57
	v_fmac_f32_e32 v100, v146, v60
	v_fmac_f32_e32 v101, v147, v61
	v_fmac_f32_e32 v172, v146, v64
	v_fmac_f32_e32 v173, v147, v65
	ds_read_b128 v[0:3], v174 offset:34176
	ds_read_b128 v[4:7], v174 offset:34432
	ds_read_b128 v[8:11], v174 offset:34688
	ds_read_b128 v[12:15], v174 offset:34944
	ds_read_b128 v[16:19], v174 offset:35200
	ds_read_b128 v[20:23], v174 offset:35456
	ds_read_b128 v[24:27], v174 offset:35712
	ds_read_b128 v[28:31], v174 offset:35968
	ds_read_b128 v[32:35], v174 offset:36224
	ds_read_b128 v[36:39], v175 offset:36992
	ds_read_b32 v40, v163 offset:36480
	ds_read_b32 v41, v163 offset:36736
	v_mul_f32_e32 v148, v78, v94
	v_mul_f32_e32 v149, v79, v94
	v_mul_f32_e32 v150, v80, v94
	v_mul_f32_e32 v151, v81, v94
	v_add_f32_e32 v168, v96, v97
	v_add_f32_e32 v166, v98, v99
	v_add_f32_e32 v169, v100, v101
	v_add_f32_e32 v170, v172, v173
	v_fmac_f32_e32 v148, v86, v95
	v_fmac_f32_e32 v149, v87, v95
	v_fmac_f32_e32 v150, v88, v95
	v_fmac_f32_e32 v151, v89, v95
	v_add_f32_dpp v168, v168, v168 row_mirror row_mask:0xf bank_mask:0xf bound_ctrl:1
	v_add_f32_dpp v166, v166, v166 row_mirror row_mask:0xf bank_mask:0xf bound_ctrl:1
	v_add_f32_dpp v169, v169, v169 row_mirror row_mask:0xf bank_mask:0xf bound_ctrl:1
	v_add_f32_dpp v170, v170, v170 row_mirror row_mask:0xf bank_mask:0xf bound_ctrl:1
	v_add_f32_dpp v168, v168, v168 row_half_mirror row_mask:0xf bank_mask:0xf bound_ctrl:1
	v_add_f32_dpp v166, v166, v166 row_half_mirror row_mask:0xf bank_mask:0xf bound_ctrl:1
	v_add_f32_dpp v169, v169, v169 row_half_mirror row_mask:0xf bank_mask:0xf bound_ctrl:1
	v_add_f32_dpp v170, v170, v170 row_half_mirror row_mask:0xf bank_mask:0xf bound_ctrl:1
	v_add_f32_dpp v168, v168, v168 quad_perm:[1,0,3,2] row_mask:0xf bank_mask:0xf bound_ctrl:1
	v_add_f32_dpp v166, v166, v166 quad_perm:[1,0,3,2] row_mask:0xf bank_mask:0xf bound_ctrl:1
	v_add_f32_dpp v169, v169, v169 quad_perm:[1,0,3,2] row_mask:0xf bank_mask:0xf bound_ctrl:1
	v_add_f32_dpp v170, v170, v170 quad_perm:[1,0,3,2] row_mask:0xf bank_mask:0xf bound_ctrl:1
	v_add_f32_dpp v168, v168, v168 quad_perm:[2,3,0,1] row_mask:0xf bank_mask:0xf bound_ctrl:1
	v_add_f32_dpp v166, v166, v166 quad_perm:[2,3,0,1] row_mask:0xf bank_mask:0xf bound_ctrl:1
	v_add_f32_dpp v169, v169, v169 quad_perm:[2,3,0,1] row_mask:0xf bank_mask:0xf bound_ctrl:1
	v_add_f32_dpp v170, v170, v170 quad_perm:[2,3,0,1] row_mask:0xf bank_mask:0xf bound_ctrl:1
	v_fma_f32 v164, v94, v91, v169
	v_fma_f32 v171, v94, v93, v170
	v_fmac_f32_e32 v148, v74, v166
	v_fmac_f32_e32 v149, v75, v166
	v_fma_f32 v167, v166, v90, v164
	v_fmac_f32_e32 v150, v76, v166
	v_fmac_f32_e32 v151, v77, v166
	v_fma_f32 v171, v166, v92, v171
	v_cndmask_b32_e64 v162, v162, v168, s[56:57]
	v_fmac_f32_e32 v148, v82, v167
	v_fmac_f32_e32 v149, v83, v167
	v_fmac_f32_e32 v150, v84, v167
	v_fmac_f32_e32 v151, v85, v167
	v_cndmask_b32_e64 v162, v162, v171, s[58:59]
	v_fma_f32 v144, v144, v70, v148
	v_fma_f32 v145, v145, v71, v149
	v_fma_f32 v146, v146, v72, v150
	v_fma_f32 v147, v147, v73, v151
	s_waitcnt lgkmcnt(0)
	v_mul_f32_e32 v96, v144, v66
	v_mul_f32_e32 v97, v145, v67
	v_mul_f32_e32 v98, v144, v0
	v_mul_f32_e32 v99, v145, v1
	v_mul_f32_e32 v100, v144, v4
	v_mul_f32_e32 v101, v145, v5
	v_mul_f32_e32 v172, v144, v8
	v_mul_f32_e32 v173, v145, v9
	v_fmac_f32_e32 v96, v146, v68
	v_fmac_f32_e32 v97, v147, v69
	v_fmac_f32_e32 v98, v146, v2
	v_fmac_f32_e32 v99, v147, v3
	v_fmac_f32_e32 v100, v146, v6
	v_fmac_f32_e32 v101, v147, v7
	v_fmac_f32_e32 v172, v146, v10
	v_fmac_f32_e32 v173, v147, v11
	ds_read_b128 v[54:57], v174 offset:37024
	ds_read_b128 v[58:61], v174 offset:37280
	ds_read_b128 v[62:65], v174 offset:37536
	ds_read_b128 v[66:69], v174 offset:37792
	ds_read_b128 v[70:73], v174 offset:38048
	ds_read_b128 v[74:77], v174 offset:38304
	ds_read_b128 v[78:81], v174 offset:38560
	ds_read_b128 v[82:85], v174 offset:38816
	ds_read_b128 v[86:89], v174 offset:39072
	ds_read_b128 v[90:93], v175 offset:39840
	ds_read_b32 v94, v163 offset:39328
	ds_read_b32 v95, v163 offset:39584
	v_mul_f32_e32 v148, v24, v40
	v_mul_f32_e32 v149, v25, v40
	v_mul_f32_e32 v150, v26, v40
	v_mul_f32_e32 v151, v27, v40
	v_add_f32_e32 v168, v96, v97
	v_add_f32_e32 v166, v98, v99
	v_add_f32_e32 v169, v100, v101
	v_add_f32_e32 v170, v172, v173
	v_fmac_f32_e32 v148, v32, v41
	v_fmac_f32_e32 v149, v33, v41
	v_fmac_f32_e32 v150, v34, v41
	v_fmac_f32_e32 v151, v35, v41
	v_add_f32_dpp v168, v168, v168 row_mirror row_mask:0xf bank_mask:0xf bound_ctrl:1
	v_add_f32_dpp v166, v166, v166 row_mirror row_mask:0xf bank_mask:0xf bound_ctrl:1
	v_add_f32_dpp v169, v169, v169 row_mirror row_mask:0xf bank_mask:0xf bound_ctrl:1
	v_add_f32_dpp v170, v170, v170 row_mirror row_mask:0xf bank_mask:0xf bound_ctrl:1
	v_add_f32_dpp v168, v168, v168 row_half_mirror row_mask:0xf bank_mask:0xf bound_ctrl:1
	v_add_f32_dpp v166, v166, v166 row_half_mirror row_mask:0xf bank_mask:0xf bound_ctrl:1
	v_add_f32_dpp v169, v169, v169 row_half_mirror row_mask:0xf bank_mask:0xf bound_ctrl:1
	v_add_f32_dpp v170, v170, v170 row_half_mirror row_mask:0xf bank_mask:0xf bound_ctrl:1
	v_add_f32_dpp v168, v168, v168 quad_perm:[1,0,3,2] row_mask:0xf bank_mask:0xf bound_ctrl:1
	v_add_f32_dpp v166, v166, v166 quad_perm:[1,0,3,2] row_mask:0xf bank_mask:0xf bound_ctrl:1
	v_add_f32_dpp v169, v169, v169 quad_perm:[1,0,3,2] row_mask:0xf bank_mask:0xf bound_ctrl:1
	v_add_f32_dpp v170, v170, v170 quad_perm:[1,0,3,2] row_mask:0xf bank_mask:0xf bound_ctrl:1
	v_add_f32_dpp v168, v168, v168 quad_perm:[2,3,0,1] row_mask:0xf bank_mask:0xf bound_ctrl:1
	v_add_f32_dpp v166, v166, v166 quad_perm:[2,3,0,1] row_mask:0xf bank_mask:0xf bound_ctrl:1
	v_add_f32_dpp v169, v169, v169 quad_perm:[2,3,0,1] row_mask:0xf bank_mask:0xf bound_ctrl:1
	v_add_f32_dpp v170, v170, v170 quad_perm:[2,3,0,1] row_mask:0xf bank_mask:0xf bound_ctrl:1
	v_fma_f32 v164, v40, v37, v169
	v_fma_f32 v171, v40, v39, v170
	v_fmac_f32_e32 v148, v20, v166
	v_fmac_f32_e32 v149, v21, v166
	v_fma_f32 v167, v166, v36, v164
	v_fmac_f32_e32 v150, v22, v166
	v_fmac_f32_e32 v151, v23, v166
	v_fma_f32 v171, v166, v38, v171
	v_cndmask_b32_e64 v162, v162, v168, s[60:61]
	v_fmac_f32_e32 v148, v28, v167
	v_fmac_f32_e32 v149, v29, v167
	v_fmac_f32_e32 v150, v30, v167
	v_fmac_f32_e32 v151, v31, v167
	v_cndmask_b32_e64 v162, v162, v171, s[62:63]
	v_fma_f32 v144, v144, v16, v148
	v_fma_f32 v145, v145, v17, v149
	v_fma_f32 v146, v146, v18, v150
	v_fma_f32 v147, v147, v19, v151
	s_waitcnt lgkmcnt(0)
	v_mul_f32_e32 v96, v144, v12
	v_mul_f32_e32 v97, v145, v13
	v_mul_f32_e32 v98, v144, v54
	v_mul_f32_e32 v99, v145, v55
	v_mul_f32_e32 v100, v144, v58
	v_mul_f32_e32 v101, v145, v59
	v_mul_f32_e32 v172, v144, v62
	v_mul_f32_e32 v173, v145, v63
	v_fmac_f32_e32 v96, v146, v14
	v_fmac_f32_e32 v97, v147, v15
	v_fmac_f32_e32 v98, v146, v56
	v_fmac_f32_e32 v99, v147, v57
	v_fmac_f32_e32 v100, v146, v60
	v_fmac_f32_e32 v101, v147, v61
	v_fmac_f32_e32 v172, v146, v64
	v_fmac_f32_e32 v173, v147, v65
	ds_read_b128 v[0:3], v174 offset:39872
	ds_read_b128 v[4:7], v174 offset:40128
	ds_read_b128 v[8:11], v174 offset:40384
	ds_read_b128 v[12:15], v174 offset:40640
	ds_read_b128 v[16:19], v174 offset:40896
	ds_read_b128 v[20:23], v174 offset:41152
	ds_read_b128 v[24:27], v174 offset:41408
	ds_read_b128 v[28:31], v174 offset:41664
	ds_read_b128 v[32:35], v174 offset:41920
	ds_read_b128 v[36:39], v175 offset:42688
	ds_read_b32 v40, v163 offset:42176
	ds_read_b32 v41, v163 offset:42432
	v_mul_f32_e32 v148, v78, v94
	v_mul_f32_e32 v149, v79, v94
	v_mul_f32_e32 v150, v80, v94
	v_mul_f32_e32 v151, v81, v94
	v_add_f32_e32 v168, v96, v97
	v_add_f32_e32 v166, v98, v99
	v_add_f32_e32 v169, v100, v101
	v_add_f32_e32 v170, v172, v173
	v_fmac_f32_e32 v148, v86, v95
	v_fmac_f32_e32 v149, v87, v95
	v_fmac_f32_e32 v150, v88, v95
	v_fmac_f32_e32 v151, v89, v95
	v_add_f32_dpp v168, v168, v168 row_mirror row_mask:0xf bank_mask:0xf bound_ctrl:1
	v_add_f32_dpp v166, v166, v166 row_mirror row_mask:0xf bank_mask:0xf bound_ctrl:1
	v_add_f32_dpp v169, v169, v169 row_mirror row_mask:0xf bank_mask:0xf bound_ctrl:1
	v_add_f32_dpp v170, v170, v170 row_mirror row_mask:0xf bank_mask:0xf bound_ctrl:1
	v_add_f32_dpp v168, v168, v168 row_half_mirror row_mask:0xf bank_mask:0xf bound_ctrl:1
	v_add_f32_dpp v166, v166, v166 row_half_mirror row_mask:0xf bank_mask:0xf bound_ctrl:1
	v_add_f32_dpp v169, v169, v169 row_half_mirror row_mask:0xf bank_mask:0xf bound_ctrl:1
	v_add_f32_dpp v170, v170, v170 row_half_mirror row_mask:0xf bank_mask:0xf bound_ctrl:1
	v_add_f32_dpp v168, v168, v168 quad_perm:[1,0,3,2] row_mask:0xf bank_mask:0xf bound_ctrl:1
	v_add_f32_dpp v166, v166, v166 quad_perm:[1,0,3,2] row_mask:0xf bank_mask:0xf bound_ctrl:1
	v_add_f32_dpp v169, v169, v169 quad_perm:[1,0,3,2] row_mask:0xf bank_mask:0xf bound_ctrl:1
	v_add_f32_dpp v170, v170, v170 quad_perm:[1,0,3,2] row_mask:0xf bank_mask:0xf bound_ctrl:1
	v_add_f32_dpp v168, v168, v168 quad_perm:[2,3,0,1] row_mask:0xf bank_mask:0xf bound_ctrl:1
	v_add_f32_dpp v166, v166, v166 quad_perm:[2,3,0,1] row_mask:0xf bank_mask:0xf bound_ctrl:1
	v_add_f32_dpp v169, v169, v169 quad_perm:[2,3,0,1] row_mask:0xf bank_mask:0xf bound_ctrl:1
	v_add_f32_dpp v170, v170, v170 quad_perm:[2,3,0,1] row_mask:0xf bank_mask:0xf bound_ctrl:1
	v_fma_f32 v164, v94, v91, v169
	v_fma_f32 v171, v94, v93, v170
	v_fmac_f32_e32 v148, v74, v166
	v_fmac_f32_e32 v149, v75, v166
	v_fma_f32 v167, v166, v90, v164
	v_fmac_f32_e32 v150, v76, v166
	v_fmac_f32_e32 v151, v77, v166
	v_fma_f32 v171, v166, v92, v171
	v_cndmask_b32_e64 v162, v162, v168, s[64:65]
	v_fmac_f32_e32 v148, v82, v167
	v_fmac_f32_e32 v149, v83, v167
	v_fmac_f32_e32 v150, v84, v167
	v_fmac_f32_e32 v151, v85, v167
	v_cndmask_b32_e64 v162, v162, v171, s[66:67]
	v_fma_f32 v144, v144, v70, v148
	v_fma_f32 v145, v145, v71, v149
	v_fma_f32 v146, v146, v72, v150
	v_fma_f32 v147, v147, v73, v151
	s_waitcnt lgkmcnt(0)
	v_mul_f32_e32 v96, v144, v66
	v_mul_f32_e32 v97, v145, v67
	v_mul_f32_e32 v98, v144, v0
	v_mul_f32_e32 v99, v145, v1
	v_mul_f32_e32 v100, v144, v4
	v_mul_f32_e32 v101, v145, v5
	v_mul_f32_e32 v172, v144, v8
	v_mul_f32_e32 v173, v145, v9
	v_fmac_f32_e32 v96, v146, v68
	v_fmac_f32_e32 v97, v147, v69
	v_fmac_f32_e32 v98, v146, v2
	v_fmac_f32_e32 v99, v147, v3
	v_fmac_f32_e32 v100, v146, v6
	v_fmac_f32_e32 v101, v147, v7
	v_fmac_f32_e32 v172, v146, v10
	v_fmac_f32_e32 v173, v147, v11
	ds_read_b128 v[54:57], v174 offset:42720
	ds_read_b128 v[58:61], v174 offset:42976
	ds_read_b128 v[62:65], v174 offset:43232
	ds_read_b128 v[66:69], v174 offset:43488
	ds_read_b128 v[70:73], v174 offset:43744
	ds_read_b128 v[74:77], v174 offset:44000
	ds_read_b128 v[78:81], v174 offset:44256
	ds_read_b128 v[82:85], v174 offset:44512
	ds_read_b128 v[86:89], v174 offset:44768
	ds_read_b128 v[90:93], v175 offset:45536
	ds_read_b32 v94, v163 offset:45024
	ds_read_b32 v95, v163 offset:45280
	v_mul_f32_e32 v148, v24, v40
	v_mul_f32_e32 v149, v25, v40
	v_mul_f32_e32 v150, v26, v40
	v_mul_f32_e32 v151, v27, v40
	v_add_f32_e32 v168, v96, v97
	v_add_f32_e32 v166, v98, v99
	v_add_f32_e32 v169, v100, v101
	v_add_f32_e32 v170, v172, v173
	v_fmac_f32_e32 v148, v32, v41
	v_fmac_f32_e32 v149, v33, v41
	v_fmac_f32_e32 v150, v34, v41
	v_fmac_f32_e32 v151, v35, v41
	v_add_f32_dpp v168, v168, v168 row_mirror row_mask:0xf bank_mask:0xf bound_ctrl:1
	v_add_f32_dpp v166, v166, v166 row_mirror row_mask:0xf bank_mask:0xf bound_ctrl:1
	v_add_f32_dpp v169, v169, v169 row_mirror row_mask:0xf bank_mask:0xf bound_ctrl:1
	v_add_f32_dpp v170, v170, v170 row_mirror row_mask:0xf bank_mask:0xf bound_ctrl:1
	v_add_f32_dpp v168, v168, v168 row_half_mirror row_mask:0xf bank_mask:0xf bound_ctrl:1
	v_add_f32_dpp v166, v166, v166 row_half_mirror row_mask:0xf bank_mask:0xf bound_ctrl:1
	v_add_f32_dpp v169, v169, v169 row_half_mirror row_mask:0xf bank_mask:0xf bound_ctrl:1
	v_add_f32_dpp v170, v170, v170 row_half_mirror row_mask:0xf bank_mask:0xf bound_ctrl:1
	v_add_f32_dpp v168, v168, v168 quad_perm:[1,0,3,2] row_mask:0xf bank_mask:0xf bound_ctrl:1
	v_add_f32_dpp v166, v166, v166 quad_perm:[1,0,3,2] row_mask:0xf bank_mask:0xf bound_ctrl:1
	v_add_f32_dpp v169, v169, v169 quad_perm:[1,0,3,2] row_mask:0xf bank_mask:0xf bound_ctrl:1
	v_add_f32_dpp v170, v170, v170 quad_perm:[1,0,3,2] row_mask:0xf bank_mask:0xf bound_ctrl:1
	v_add_f32_dpp v168, v168, v168 quad_perm:[2,3,0,1] row_mask:0xf bank_mask:0xf bound_ctrl:1
	v_add_f32_dpp v166, v166, v166 quad_perm:[2,3,0,1] row_mask:0xf bank_mask:0xf bound_ctrl:1
	v_add_f32_dpp v169, v169, v169 quad_perm:[2,3,0,1] row_mask:0xf bank_mask:0xf bound_ctrl:1
	v_add_f32_dpp v170, v170, v170 quad_perm:[2,3,0,1] row_mask:0xf bank_mask:0xf bound_ctrl:1
	v_fma_f32 v164, v40, v37, v169
	v_fma_f32 v171, v40, v39, v170
	v_fmac_f32_e32 v148, v20, v166
	v_fmac_f32_e32 v149, v21, v166
	v_fma_f32 v167, v166, v36, v164
	v_fmac_f32_e32 v150, v22, v166
	v_fmac_f32_e32 v151, v23, v166
	v_fma_f32 v171, v166, v38, v171
	v_cndmask_b32_e64 v162, v162, v168, s[68:69]
	v_fmac_f32_e32 v148, v28, v167
	v_fmac_f32_e32 v149, v29, v167
	v_fmac_f32_e32 v150, v30, v167
	v_fmac_f32_e32 v151, v31, v167
	v_cndmask_b32_e64 v162, v162, v171, s[70:71]
	v_fma_f32 v144, v144, v16, v148
	v_fma_f32 v145, v145, v17, v149
	v_fma_f32 v146, v146, v18, v150
	v_fma_f32 v147, v147, v19, v151
	s_waitcnt lgkmcnt(0)
	v_mul_f32_e32 v96, v144, v12
	v_mul_f32_e32 v97, v145, v13
	v_mul_f32_e32 v98, v144, v54
	v_mul_f32_e32 v99, v145, v55
	v_mul_f32_e32 v100, v144, v58
	v_mul_f32_e32 v101, v145, v59
	v_mul_f32_e32 v172, v144, v62
	v_mul_f32_e32 v173, v145, v63
	v_fmac_f32_e32 v96, v146, v14
	v_fmac_f32_e32 v97, v147, v15
	v_fmac_f32_e32 v98, v146, v56
	v_fmac_f32_e32 v99, v147, v57
	v_fmac_f32_e32 v100, v146, v60
	v_fmac_f32_e32 v101, v147, v61
	v_fmac_f32_e32 v172, v146, v64
	v_fmac_f32_e32 v173, v147, v65
	v_mul_f32_e32 v148, v78, v94
	v_mul_f32_e32 v149, v79, v94
	v_mul_f32_e32 v150, v80, v94
	v_mul_f32_e32 v151, v81, v94
	v_add_f32_e32 v168, v96, v97
	v_add_f32_e32 v166, v98, v99
	v_add_f32_e32 v169, v100, v101
	v_add_f32_e32 v170, v172, v173
	v_fmac_f32_e32 v148, v86, v95
	v_fmac_f32_e32 v149, v87, v95
	v_fmac_f32_e32 v150, v88, v95
	v_fmac_f32_e32 v151, v89, v95
	v_add_f32_dpp v168, v168, v168 row_mirror row_mask:0xf bank_mask:0xf bound_ctrl:1
	v_add_f32_dpp v166, v166, v166 row_mirror row_mask:0xf bank_mask:0xf bound_ctrl:1
	v_add_f32_dpp v169, v169, v169 row_mirror row_mask:0xf bank_mask:0xf bound_ctrl:1
	v_add_f32_dpp v170, v170, v170 row_mirror row_mask:0xf bank_mask:0xf bound_ctrl:1
	v_add_f32_dpp v168, v168, v168 row_half_mirror row_mask:0xf bank_mask:0xf bound_ctrl:1
	v_add_f32_dpp v166, v166, v166 row_half_mirror row_mask:0xf bank_mask:0xf bound_ctrl:1
	v_add_f32_dpp v169, v169, v169 row_half_mirror row_mask:0xf bank_mask:0xf bound_ctrl:1
	v_add_f32_dpp v170, v170, v170 row_half_mirror row_mask:0xf bank_mask:0xf bound_ctrl:1
	v_add_f32_dpp v168, v168, v168 quad_perm:[1,0,3,2] row_mask:0xf bank_mask:0xf bound_ctrl:1
	v_add_f32_dpp v166, v166, v166 quad_perm:[1,0,3,2] row_mask:0xf bank_mask:0xf bound_ctrl:1
	v_add_f32_dpp v169, v169, v169 quad_perm:[1,0,3,2] row_mask:0xf bank_mask:0xf bound_ctrl:1
	v_add_f32_dpp v170, v170, v170 quad_perm:[1,0,3,2] row_mask:0xf bank_mask:0xf bound_ctrl:1
	v_add_f32_dpp v168, v168, v168 quad_perm:[2,3,0,1] row_mask:0xf bank_mask:0xf bound_ctrl:1
	v_add_f32_dpp v166, v166, v166 quad_perm:[2,3,0,1] row_mask:0xf bank_mask:0xf bound_ctrl:1
	v_add_f32_dpp v169, v169, v169 quad_perm:[2,3,0,1] row_mask:0xf bank_mask:0xf bound_ctrl:1
	v_add_f32_dpp v170, v170, v170 quad_perm:[2,3,0,1] row_mask:0xf bank_mask:0xf bound_ctrl:1
	v_fma_f32 v164, v94, v91, v169
	v_fma_f32 v171, v94, v93, v170
	v_fmac_f32_e32 v148, v74, v166
	v_fmac_f32_e32 v149, v75, v166
	v_fma_f32 v167, v166, v90, v164
	v_fmac_f32_e32 v150, v76, v166
	v_fmac_f32_e32 v151, v77, v166
	v_fma_f32 v171, v166, v92, v171
	v_cndmask_b32_e64 v162, v162, v168, s[44:45]
	v_fmac_f32_e32 v148, v82, v167
	v_fmac_f32_e32 v149, v83, v167
	v_fmac_f32_e32 v150, v84, v167
	v_fmac_f32_e32 v151, v85, v167
	v_cndmask_b32_e64 v162, v162, v171, s[42:43]
	v_fma_f32 v144, v144, v70, v148
	v_fma_f32 v145, v145, v71, v149
	v_fma_f32 v146, v146, v72, v150
	v_fma_f32 v147, v147, v73, v151
	v_mov_b64_e32 v[24:25], v[66:67]
	v_mov_b64_e32 v[26:27], v[68:69]
	s_mov_b64 s[92:93], 0
